# mixer B: the LDS copy of the compressed K/V^T is kept across consecutive B units of a workgroup (same batch/kv head within a P7 instance): a per-wave flag skips the reload, the LDS writes and the extr
# speedup vs baseline: 1.0071x; 1.0001x over previous
.LBB0_383:
	s_or_b64 exec, exec, s[4:5]
	s_add_u32 s60, s74, 0x7000000
	s_mul_i32 s4, s6, 3
	s_addc_u32 s61, s75, 0
	v_writelane_b32 v255, s4, 7
	s_lshl_b32 s4, s73, 4
	v_writelane_b32 v255, s4, 8
	s_mov_b32 s4, 0
	s_nop 0
	v_writelane_b32 v255, s4, 61
	s_add_u32 s4, s74, 0x11600000
	v_writelane_b32 v255, s4, 9
	s_addc_u32 s4, s75, 0
	v_writelane_b32 v255, s4, 10
	s_add_u32 s4, s74, 0x12200000
	v_writelane_b32 v255, s4, 11
	s_addc_u32 s4, s75, 0
	v_writelane_b32 v255, s4, 12
	s_add_u32 s4, s74, 0x12e00000
	v_writelane_b32 v255, s4, 13
	s_addc_u32 s4, s75, 0
	v_writelane_b32 v255, s4, 14
	s_add_u32 s4, s74, 0x9400000
	v_writelane_b32 v255, s4, 15
	s_addc_u32 s4, s75, 0
	v_writelane_b32 v255, s4, 16
	s_add_u32 s4, s74, 0xb800000
	v_writelane_b32 v255, s4, 17
	s_addc_u32 s4, s75, 0
	s_and_b32 s8, s73, 3
	s_lshl_b32 s9, s8, 6
	s_lshl_b32 s10, s8, 10
	v_writelane_b32 v255, s4, 18
	s_add_u32 s4, s74, 0x19a00000
	s_addc_u32 s5, s75, 0
	v_writelane_b32 v255, s4, 19
	s_lshl_b32 s92, s37, 18
	s_lshr_b32 s11, s6, 1
	v_writelane_b32 v255, s5, 20
	s_lshl_b64 s[4:5], s[92:93], 2
	s_add_u32 s4, s74, s4
	s_addc_u32 s5, s75, s5
	s_add_u32 s4, s4, 0x100000
	v_writelane_b32 v255, s37, 21
	s_addc_u32 s5, s5, 0
	v_writelane_b32 v255, s4, 22
	s_lshl_b32 s68, s73, 2
	s_nop 0
	v_writelane_b32 v255, s5, 23
	s_lshl_b32 s4, s7, 2
	s_and_b32 s4, s4, 4
	v_writelane_b32 v255, s4, 24
	s_lshl_b32 s4, s11, 12
	s_mov_b32 s5, s93
	v_writelane_b32 v255, s4, 25
	s_nop 1
	v_writelane_b32 v255, s5, 26
	s_add_u32 s4, s74, 0x11400000
	s_addc_u32 s5, s75, 0
	v_writelane_b32 v255, s4, 27
	s_nop 1
	v_writelane_b32 v255, s5, 28
	s_add_u32 s4, s74, 0xdc00000
	s_addc_u32 s5, s75, 0
	v_writelane_b32 v255, s4, 29
	s_nop 1
	v_writelane_b32 v255, s5, 30
	s_lshl_b32 s4, s11, 21
	s_lshl_b32 s5, s6, 19
	s_add_u32 s5, s74, s5
	s_addc_u32 s7, s75, 0
	s_add_u32 s64, s5, 0x10400000
	s_addc_u32 s65, s7, 0
	s_add_u32 s12, s5, 0x10800000
	s_addc_u32 s13, s7, 0
	s_lshl_b32 s6, s6, 15
	s_add_u32 s6, s74, s6
	s_addc_u32 s11, s75, 0
	s_add_u32 s42, s6, 0x2e00000
	v_writelane_b32 v255, s12, 31
	s_addc_u32 s43, s11, 0
	s_nop 0
	v_writelane_b32 v255, s13, 32
	s_add_u32 s12, s6, 0x2e80000
	s_addc_u32 s13, s11, 0
	v_writelane_b32 v255, s12, 33
	s_lshl_b32 s6, s73, 10
	s_add_i32 s6, s6, 0
	v_writelane_b32 v255, s13, 34
	v_writelane_b32 v255, s6, 35
	s_lshl_b32 s6, s73, 3
	s_add_i32 s6, s6, 0
	s_add_u32 s66, s5, 0x10c00000
	s_addc_u32 s67, s7, 0
	v_writelane_b32 v255, s6, 36
	s_add_u32 s6, s5, 0x11000000
	s_addc_u32 s7, s7, 0
	v_writelane_b32 v255, s6, 37
	s_nop 1
	v_writelane_b32 v255, s7, 38
	s_add_u32 s6, s74, 0x9402000
	s_addc_u32 s7, s75, 0
	v_writelane_b32 v255, s6, 39
	s_add_u32 s5, s74, 0xb800080
	s_nop 0
	v_writelane_b32 v255, s7, 40
	v_writelane_b32 v255, s5, 41
	s_addc_u32 s5, s75, 0
	v_writelane_b32 v255, s5, 42
	s_sub_i32 s5, s73, 51
	v_writelane_b32 v255, s5, 43
	s_lshl_b32 s5, s8, 11
	s_add_u32 s5, s74, s5
	v_writelane_b32 v255, s5, 44
	s_addc_u32 s5, s75, 0
	v_writelane_b32 v255, s5, 45
	s_add_i32 s5, s68, 0xfad
	v_writelane_b32 v255, s5, 46
	s_lshl_b32 s5, s9, 1
	v_writelane_b32 v255, s5, 47
	s_lshl_b32 s6, s10, 1
	v_writelane_b32 v255, s6, 48
	s_lshl_b32 s4, s4, 1
	s_nop 0
	v_writelane_b32 v255, s7, 49
	v_writelane_b32 v255, s4, 50
	s_branch .LBB0_388

.LBB0_414:
	v_readlane_b32 s100, v255, 33
	v_readlane_b32 s101, v255, 34
	v_add_u32_e32 v172, s63, v115
	v_lshlrev_b32_e32 v173, 4, v172
	v_add_u32_e32 v174, 0x2000, v173
	v_add_u32_e32 v175, 0x4000, v173
	v_add_u32_e32 v176, 0x6000, v173
	s_nop 0
	v_readlane_b32 vcc_lo, v255, 61
	s_nop 0
	s_cmp_lg_u32 vcc_lo, 0
	s_cbranch_scc1 .Lck_noload
	global_load_dwordx4 v[140:143], v173, s[42:43]
	global_load_dwordx4 v[144:147], v174, s[42:43]
	global_load_dwordx4 v[148:151], v175, s[42:43]
	global_load_dwordx4 v[152:155], v176, s[42:43]
	global_load_dwordx4 v[156:159], v173, s[100:101]
	global_load_dwordx4 v[160:163], v174, s[100:101]
	global_load_dwordx4 v[164:167], v175, s[100:101]
	global_load_dwordx4 v[168:171], v176, s[100:101]
.Lck_noload:
	v_lshrrev_b32_e32 v177, 3, v172
	v_and_b32_e32 v179, 7, v172
	v_mul_u32_u24_e32 v177, 0x90, v177
	v_lshl_add_u32 v177, v179, 4, v177
	v_add_u32_e32 v177, 0xe000, v177
	v_lshrrev_b32_e32 v178, 5, v172
	v_and_b32_e32 v179, 31, v172
	v_mul_u32_u24_e32 v178, 0x220, v178
	v_lshl_add_u32 v178, v179, 4, v178
	v_add_u32_e32 v178, 0x17000, v178
	v_and_b32_e32 v179, 15, v115
	v_lshrrev_b32_e32 v180, 4, v115
	v_mul_u32_u24_e32 v252, 0x90, v179
	v_lshl_add_u32 v252, v180, 4, v252
	v_add_u32_e32 v252, 0xe000, v252
	v_mul_u32_u24_e32 v253, 0x220, v179
	v_lshl_add_u32 v253, v180, 4, v253
	v_add_u32_e32 v253, 0x17000, v253
	v_bfe_u32 v218, v115, 2, 2
	s_lshl_b32 s57, s69, 5
	v_and_b32_e32 v203, 3, v115
	v_or_b32_e32 v202, s68, v218
	s_sub_i32 s58, 0xfe0, s57
	v_readlane_b32 s6, v255, 24
	v_add_u32_e32 v126, s58, v202
	v_ashrrev_i32_e32 v127, 31, v126
	v_or_b32_e32 v117, s6, v203
	v_readlane_b32 s6, v255, 25
	v_readlane_b32 s7, v255, 26
	s_movk_i32 s8, 0x60
	v_mul_u32_u24_e32 v2, 3, v117
	v_lshl_add_u64 v[118:119], v[126:127], 0, s[6:7]
	v_readlane_b32 s6, v255, 27
	v_readlane_b32 s7, v255, 28
	v_lshlrev_b32_e32 v136, 2, v2
	v_ashrrev_i32_e32 v125, 4, v115
	v_mov_b64_e32 v[0:1], s[6:7]
	v_mad_u64_u32 v[0:1], s[6:7], v118, s8, v[0:1]
	v_mad_i32_i24 v1, v119, s8, v1
	v_readlane_b32 s6, v255, 50
	v_lshl_add_u64 v[6:7], v[0:1], 0, v[136:137]
	v_add_u32_e32 v10, s63, v115
	v_lshl_or_b32 v136, v117, 19, s6
	v_readlane_b32 s6, v255, 29
	v_readlane_b32 s7, v255, 30
	v_lshlrev_b64 v[2:3], 7, v[126:127]
	v_lshlrev_b32_e32 v4, 3, v125
	v_lshl_add_u64 v[0:1], s[6:7], 0, v[136:137]
	v_readlane_b32 s6, v255, 22
	v_lshl_add_u64 v[0:1], v[0:1], 0, v[2:3]
	v_ashrrev_i32_e32 v5, 31, v4
	v_lshlrev_b64 v[8:9], 6, v[118:119]
	v_readlane_b32 s7, v255, 23
	v_ashrrev_i32_e32 v120, 3, v10
	v_lshl_add_u64 v[0:1], v[4:5], 1, v[0:1]
	v_lshl_add_u64 v[8:9], s[6:7], 0, v[8:9]
	v_ashrrev_i32_e32 v121, 31, v120
	v_lshlrev_b32_e32 v10, 3, v115
	global_load_dwordx4 v[36:39], v[0:1], off
	s_nop 0
	global_load_dwordx4 v[0:3], v[0:1], off offset:64
	s_waitcnt vmcnt(0)
	global_load_dwordx4 v[44:47], v[8:9], off
	global_load_dwordx4 v[32:35], v[8:9], off offset:16
	global_load_dwordx4 v[40:43], v[8:9], off offset:32
	global_load_dwordx4 v[28:31], v[8:9], off offset:48
	v_lshlrev_b64 v[8:9], 7, v[120:121]
	v_and_b32_e32 v124, 56, v10
	v_lshl_add_u64 v[8:9], s[64:65], 0, v[8:9]
	v_lshlrev_b32_e32 v136, 1, v124
	v_readlane_b32 s6, v255, 31
	v_lshl_add_u64 v[8:9], v[8:9], 0, v[136:137]
	v_lshlrev_b64 v[122:123], 13, v[120:121]
	v_readlane_b32 s7, v255, 32
	global_load_dwordx4 v[20:23], v[8:9], off
	s_add_i32 s56, s58, s68
	v_lshl_add_u64 v[8:9], s[6:7], 0, v[122:123]
	v_lshl_add_u64 v[128:129], v[8:9], 0, v[136:137]
	global_load_dwordx3 v[112:114], v[6:7], off
	global_load_dwordx4 v[24:27], v[128:129], off
	s_sub_i32 s7, s56, 28
	s_ashr_i32 s7, s7, 8
	s_or_b32 s6, s56, 3
	s_add_i32 s7, s7, 1
	s_cmp_gt_i32 s6, 30
	v_and_b32_e32 v121, 15, v115
	s_cselect_b32 s40, s7, 0
	v_lshlrev_b32_e32 v6, 6, v121
	s_cmp_gt_i32 s40, 0
	s_cselect_b64 s[38:39], -1, 0
	s_cmp_lt_i32 s40, 1
	v_lshlrev_b32_e32 v6, 1, v6
	s_cmp_gt_i32 s40, 1
	s_cselect_b64 s[20:21], -1, 0
	s_cmp_gt_i32 s40, 2
	s_cselect_b64 s[36:37], -1, 0
	s_cmp_gt_i32 s40, 3
	s_cselect_b64 s[18:19], -1, 0
	s_cmp_gt_i32 s40, 4
	s_cselect_b64 s[34:35], -1, 0
	s_cmp_gt_i32 s40, 5
	s_cselect_b64 s[16:17], -1, 0
	s_cmp_gt_i32 s40, 6
	s_cselect_b64 s[30:31], -1, 0
	s_cmp_gt_i32 s40, 7
	s_cselect_b64 s[14:15], -1, 0
	s_cmp_gt_i32 s40, 8
	s_cselect_b64 s[28:29], -1, 0
	s_cmp_gt_i32 s40, 9
	s_cselect_b64 s[12:13], -1, 0
	s_cmp_gt_i32 s40, 10
	s_cselect_b64 s[26:27], -1, 0
	s_cmp_gt_i32 s40, 11
	s_cselect_b64 s[10:11], -1, 0
	s_cmp_gt_i32 s40, 12
	s_cselect_b64 s[24:25], -1, 0
	s_cmp_gt_i32 s40, 13
	s_cselect_b64 s[8:9], -1, 0
	s_cmp_gt_i32 s40, 14
	s_cselect_b64 s[22:23], -1, 0
	s_cmp_gt_i32 s40, 15
	s_cselect_b64 s[6:7], -1, 0
	v_mov_b32_e32 v7, v137
	v_lshl_add_u64 v[138:139], s[42:43], 0, v[6:7]
	v_lshl_add_u64 v[138:139], v[4:5], 1, v[138:139]
	v_add_co_u32_e32 v138, vcc, 0x1000, v138
	s_nop 1
	v_addc_co_u32_e32 v139, vcc, 0, v139, vcc
	v_readlane_b32 vcc_lo, v255, 61
	s_nop 0
	s_cmp_lg_u32 vcc_lo, 0
	s_cbranch_scc1 .Lck_nowrite
	s_waitcnt vmcnt(0)
	ds_write_b128 v177, v[140:143]
	ds_write_b128 v177, v[144:147] offset:9216
	ds_write_b128 v177, v[148:151] offset:18432
	ds_write_b128 v177, v[152:155] offset:27648
	ds_write_b128 v178, v[156:159]
	ds_write_b128 v178, v[160:163] offset:8704
	ds_write_b128 v178, v[164:167] offset:17408
	ds_write_b128 v178, v[168:171] offset:26112
	s_waitcnt lgkmcnt(0)
	s_barrier
	s_mov_b32 vcc_lo, 1
	s_nop 0
	v_writelane_b32 v255, vcc_lo, 61
.Lck_nowrite:
	s_cmp_lt_i32 s40, 1
	s_cbranch_scc1 .Lcq_issued
	ds_read_b128 v[48:51], v252
	ds_read_b128 v[140:143], v252 offset:64
	s_cmp_lt_i32 s40, 2
	s_cbranch_scc1 .Lcq_issued
	ds_read_b128 v[52:55], v252 offset:2304
	ds_read_b128 v[144:147], v252 offset:2368
	s_cmp_lt_i32 s40, 3
	s_cbranch_scc1 .Lcq_issued
	ds_read_b128 v[56:59], v252 offset:4608
	ds_read_b128 v[148:151], v252 offset:4672
	s_cmp_lt_i32 s40, 4
	s_cbranch_scc1 .Lcq_issued
	ds_read_b128 v[60:63], v252 offset:6912
	ds_read_b128 v[152:155], v252 offset:6976
	v_add_co_u32_e32 v138, vcc, 0x2000, v138
	s_nop 1
	v_addc_co_u32_e32 v139, vcc, 0, v139, vcc
	s_cmp_lt_i32 s40, 5
	s_cbranch_scc1 .Lcq_issued
	ds_read_b128 v[64:67], v252 offset:9216
	ds_read_b128 v[156:159], v252 offset:9280
	s_cmp_lt_i32 s40, 6
	s_cbranch_scc1 .Lcq_issued
	ds_read_b128 v[68:71], v252 offset:11520
	ds_read_b128 v[160:163], v252 offset:11584
	s_cmp_lt_i32 s40, 7
	s_cbranch_scc1 .Lcq_issued
	ds_read_b128 v[72:75], v252 offset:13824
	ds_read_b128 v[164:167], v252 offset:13888
	s_cmp_lt_i32 s40, 8
	s_cbranch_scc1 .Lcq_issued
	ds_read_b128 v[76:79], v252 offset:16128
	ds_read_b128 v[168:171], v252 offset:16192
	v_add_co_u32_e32 v138, vcc, 0x2000, v138
	s_nop 1
	v_addc_co_u32_e32 v139, vcc, 0, v139, vcc
	s_cmp_lt_i32 s40, 9
	s_cbranch_scc1 .Lcq_issued
	ds_read_b128 v[80:83], v252 offset:18432
	ds_read_b128 v[172:175], v252 offset:18496
	s_cmp_lt_i32 s40, 10
	s_cbranch_scc1 .Lcq_issued
	ds_read_b128 v[84:87], v252 offset:20736
	ds_read_b128 v[176:179], v252 offset:20800
	s_cmp_lt_i32 s40, 11
	s_cbranch_scc1 .Lcq_issued
	ds_read_b128 v[88:91], v252 offset:23040
	ds_read_b128 v[180:183], v252 offset:23104
	s_cmp_lt_i32 s40, 12
	s_cbranch_scc1 .Lcq_issued
	ds_read_b128 v[92:95], v252 offset:25344
	ds_read_b128 v[184:187], v252 offset:25408
	v_add_co_u32_e32 v138, vcc, 0x2000, v138
	s_nop 1
	v_addc_co_u32_e32 v139, vcc, 0, v139, vcc
	s_cmp_lt_i32 s40, 13
	s_cbranch_scc1 .Lcq_issued
	ds_read_b128 v[96:99], v252 offset:27648
	ds_read_b128 v[188:191], v252 offset:27712
	s_cmp_lt_i32 s40, 14
	s_cbranch_scc1 .Lcq_issued
	ds_read_b128 v[100:103], v252 offset:29952
	ds_read_b128 v[192:195], v252 offset:30016
	s_cmp_lt_i32 s40, 15
	s_cbranch_scc1 .Lcq_issued
	ds_read_b128 v[104:107], v252 offset:32256
	ds_read_b128 v[196:199], v252 offset:32320
	s_cmp_lt_i32 s40, 16
	s_cbranch_scc1 .Lcq_issued
	ds_read_b128 v[108:111], v252 offset:34560
	ds_read_b128 v[204:207], v252 offset:34624

.LBB0_617:
	v_lshrrev_b32_e32 v210, 3, v111
	v_lshl_add_u32 v210, v112, 1, v210
	v_and_b32_e32 v211, 7, v111
	v_lshlrev_b32_e32 v208, 4, v211
	v_mov_b32_e32 v209, v137
	v_lshlrev_b32_e32 v212, 3, v211
	v_mov_b32_e32 v213, v137
	v_mov_b32_e32 v214, 0x10000
	v_mov_b32_e32 v215, v137
	v_mov_b32_e32 v232, 0x1000
	v_mov_b32_e32 v233, v137
	s_mov_b32 s100, 0
	s_nop 0
	v_writelane_b32 v255, s100, 61
	v_readlane_b32 s100, v255, 8
	s_nop 0
	s_mul_i32 s100, s100, 0x280
	s_add_i32 s100, s100, 0x4000
	v_mul_u32_u24_e32 v234, 0xa0, v210
	v_lshl_add_u32 v234, v211, 4, v234
	v_add_u32_e32 v234, s100, v234
	v_mul_u32_u24_e32 v235, 0xa0, v111
	v_lshl_add_u32 v235, v112, 4, v235
	v_add_u32_e32 v235, s100, v235
	s_ashr_i32 s6, s45, 2
	s_max_i32 s6, s6, 0x80
	s_add_i32 s56, s45, 0xf0
	s_addk_i32 s6, 0xff80
	v_lshlrev_b32_e32 v16, 12, v210
	s_ashr_i32 s57, s56, 8
	s_lshr_b32 s58, s6, 6
	v_lshlrev_b64 v[92:93], 1, v[90:91]
	s_mov_b64 s[78:79], 0x40000
	s_movk_i32 s84, 0x121
	s_cmp_gt_i32 s58, s57
	v_lshl_add_u64 v[98:99], v[32:33], 0, v[92:93]
	v_lshlrev_b32_e32 v96, 1, v16
	v_lshlrev_b32_e32 v94, 13, v210
	s_cbranch_scc1 .LBB0_622
	v_add_co_u32_e32 v20, vcc, 0xc00000, v98
	v_readlane_b32 s7, v255, 47
	s_nop 0
	v_addc_co_u32_e32 v21, vcc, 0, v99, vcc
	global_load_dwordx4 v[16:19], v[20:21], off
	s_nop 0
	global_load_dwordx4 v[20:23], v[20:21], off offset:64
	v_lshl_or_b32 v136, v210, 9, s7
	v_readlane_b32 s10, v255, 48
	s_waitcnt vmcnt(0)
	v_lshl_add_u64 v[24:25], s[38:39], 0, v[136:137]
	s_mov_b64 s[8:9], 0xc00000
	v_mov_b32_e32 v97, v137
	v_readlane_b32 s11, v255, 49
	v_lshl_add_u64 v[100:101], v[24:25], 0, s[8:9]
	v_lshl_add_u64 v[24:25], s[52:53], 0, v[96:97]
	s_mov_b32 s11, s93
	s_mov_b32 s12, s10
	v_writelane_b32 v255, s12, 48
	v_lshl_add_u64 v[24:25], v[24:25], 0, s[10:11]
	v_lshl_add_u64 v[24:25], v[24:25], 0, v[208:209]
	v_writelane_b32 v255, s13, 49
	s_mov_b32 s41, s93
	s_lshr_b32 s92, s6, 6
	v_lshl_add_u64 v[102:103], v[24:25], 0, s[8:9]
	s_and_b32 s54, s6, 0xffffffc0
	s_lshl_b64 s[8:9], s[40:41], 19
	s_lshl_b64 s[6:7], s[92:93], 7
	v_readlane_b32 s10, v255, 44
	s_add_u32 s6, s10, s6
	v_readlane_b32 s10, v255, 45
	s_addc_u32 s7, s10, s7
	s_add_u32 s6, s6, s8
	v_mov_b32_e32 v95, v137
	s_addc_u32 s7, s7, s9
	v_lshl_add_u64 v[104:105], s[6:7], 0, v[94:95]
	s_lshl_b64 s[6:7], s[92:93], 15
	s_add_u32 s6, s8, s6
	v_ashrrev_i32_e32 v26, 2, v88
	v_lshlrev_b32_e32 v24, 2, v112
	s_addc_u32 s7, s9, s7
	v_add_u32_e32 v25, s54, v24
	v_sub_u32_e32 v24, v26, v24
	s_add_u32 s6, s74, s6
	v_subrev_u32_e32 v24, s54, v24
	s_addc_u32 s7, s75, s7
	v_sub_u32_e32 v97, v25, v26
	v_add_u32_e32 v116, 0xffffff9d, v24
	v_lshl_add_u64 v[106:107], s[6:7], 0, v[136:137]
	s_mov_b32 s92, s58
	s_branch .LBB0_620
